# P10: next work-queue item popped at the tile-loop exit so the atomic round trip hides behind the last P V and the epilogue
# baseline (speedup 1.0000x reference)
.LBB0_1218:
	s_mov_b32 s100, 0
	s_cmp_lt_i32 s44, 11
	s_cselect_b64 s[8:9], -1, 0
	s_and_b64 s[22:23], s[8:9], s[6:7]
	s_andn2_b64 vcc, exec, s[22:23]
	s_cbranch_vccnz .LBB0_1363
	s_add_u32 s3, s42, 0x14804000
	s_addc_u32 s56, s43, 0
	s_add_u32 s57, s42, 0x19004000
	s_addc_u32 s58, s43, 0
	s_add_u32 s59, s42, 0x11804000
	s_addc_u32 s60, s43, 0
	s_add_u32 s61, s42, 0x9004000
	s_addc_u32 s62, s43, 0
	s_add_u32 s63, s42, 0x5004000
	s_addc_u32 s64, s43, 0
	s_add_u32 s65, s42, 0x4944000
	s_addc_u32 s66, s43, 0
	s_add_u32 s67, s42, 0x4a44000
	v_mul_u32_u24_e32 v1, 0x110, v212
	s_addc_u32 s68, s43, 0
	v_add_u32_e32 v0, 0xc800, v215
	s_movk_i32 s70, 0x90
	v_mul_u32_u24_e32 v149, 0x90, v212
	v_add_u32_e32 v146, 0, v214
	v_and_b32_e32 v2, 15, v213
	v_lshlrev_b32_e32 v200, 2, v227
	s_add_i32 s71, 0, 0x20010
	v_lshlrev_b32_e32 v152, 1, v214
	v_add_u32_e32 v214, v215, v1
	v_mbcnt_lo_u32_b32 v1, -1, 0
	v_mov_b32_e32 v145, 0
	v_lshlrev_b32_e32 v147, 4, v228
	s_mov_b32 s25, 0
	s_movk_i32 s69, 0x110
	v_mad_u32_u24 v151, v212, s70, v215
	v_lshl_add_u32 v148, v2, 4, 0
	v_lshlrev_b32_e32 v150, 3, v2
	v_bfe_u32 v199, v213, 4, 2
	v_mul_u32_u24_e32 v201, 0x190, v212
	v_mov_b32_e32 v236, s71
	s_movk_i32 s72, 0x1e00
	s_movk_i32 s73, 0x180
	s_mov_b32 s74, 0x78787879
	s_movk_i32 s75, 0x100
	s_mov_b32 s76, 0x38e38e39
	s_movk_i32 s77, 0x80
	s_add_i32 s78, 0, 0xa400
	s_mov_b64 s[26:27], 0x80
	s_mov_b64 s[28:29], 0x100
	s_mov_b32 s79, 0x41000000
	s_mov_b64 s[30:31], 0x180
	s_mov_b64 s[34:35], 0x1400
	s_movk_i32 s80, 0x1200
	s_mov_b32 s81, 0x51eb851f
	s_mov_b64 s[36:37], 0x48000
	s_add_i32 s83, 0, 0xc400
	v_mbcnt_hi_u32_b32 v237, -1, v1
	v_add_u32_e32 v238, v0, v149
	v_mov_b32_e32 v239, 0xff800000
	s_branch .LBB0_1223

.LBB0_1223:
	s_and_saveexec_b64 s[6:7], s[4:5]
	s_cbranch_execz .LBB0_1227
	s_mov_b64 s[10:11], exec
	v_mbcnt_lo_u32_b32 v0, s10, 0
	v_mbcnt_hi_u32_b32 v0, s11, v0
	v_cmp_eq_u32_e32 vcc, 0, v0
	s_and_saveexec_b64 s[8:9], vcc
	s_cbranch_execz .LBB0_1226
	s_bcnt1_i32_b64 s10, s[10:11]
	v_mov_b32_e32 v1, s10
	s_cmp_lg_u32 s100, 0
	s_cbranch_scc1 .Lpop_pref
	global_atomic_add v1, v145, v1, s[42:43] sc0
	s_branch .LBB0_1226
.Lpop_pref:
	s_waitcnt vmcnt(0)
	v_mov_b32_e32 v1, v253
.LBB0_1226:
	s_or_b64 exec, exec, s[8:9]
	s_mov_b32 s100, 0
	s_waitcnt vmcnt(0)
	v_readfirstlane_b32 s8, v1
	v_mov_b32_e32 v1, s71
	s_nop 0
	v_add_u32_e32 v0, s8, v0
	ds_write_b32 v1, v0

.LBB0_1340:
	s_mov_b64 exec, s[4:5]
	v_mov_b32_e32 v254, 1
	global_atomic_add v253, v145, v254, s[42:43] sc0
	s_mov_b64 exec, -1
	s_mov_b32 s100, 1
	s_cmp_eq_u32 s88, 0
	s_cbranch_scc1 .Lfa_exit2
	s_mul_i32 s33, s86, 0x4800
	v_add_u32_e32 v211, s33, v151
	ds_read_b128 v[232:235], v211 offset:51200
	ds_read_b128 v[202:205], v211 offset:55808
	ds_read_b128 v[206:209], v211 offset:60416
	ds_read_b128 v[244:247], v211 offset:65024
	s_waitcnt lgkmcnt(3)
	v_mfma_f32_32x32x16_bf16 v[48:63], v[232:235], v[216:219], v[48:63]
	ds_read_b128 v[232:235], v211 offset:51232
	s_waitcnt lgkmcnt(3)
	v_mfma_f32_32x32x16_bf16 v[32:47], v[202:205], v[216:219], v[32:47]
	ds_read_b128 v[202:205], v211 offset:55840
	s_waitcnt lgkmcnt(3)
	v_mfma_f32_32x32x16_bf16 v[16:31], v[206:209], v[216:219], v[16:31]
	ds_read_b128 v[206:209], v211 offset:60448
	s_waitcnt lgkmcnt(3)
	v_mfma_f32_32x32x16_bf16 v[0:15], v[244:247], v[216:219], v[0:15]
	ds_read_b128 v[244:247], v211 offset:65056
	s_waitcnt lgkmcnt(3)
	v_mfma_f32_32x32x16_bf16 v[48:63], v[232:235], v[220:223], v[48:63]
	ds_read_b128 v[232:235], v211 offset:51264
	s_waitcnt lgkmcnt(3)
	v_mfma_f32_32x32x16_bf16 v[32:47], v[202:205], v[220:223], v[32:47]
	ds_read_b128 v[202:205], v211 offset:55872
	s_waitcnt lgkmcnt(3)
	v_mfma_f32_32x32x16_bf16 v[16:31], v[206:209], v[220:223], v[16:31]
	ds_read_b128 v[206:209], v211 offset:60480
	s_waitcnt lgkmcnt(3)
	v_mfma_f32_32x32x16_bf16 v[0:15], v[244:247], v[220:223], v[0:15]
	ds_read_b128 v[244:247], v211 offset:65088
	s_waitcnt lgkmcnt(3)
	v_mfma_f32_32x32x16_bf16 v[48:63], v[232:235], v[224:227], v[48:63]
	ds_read_b128 v[232:235], v211 offset:51296
	s_waitcnt lgkmcnt(3)
	v_mfma_f32_32x32x16_bf16 v[32:47], v[202:205], v[224:227], v[32:47]
	ds_read_b128 v[202:205], v211 offset:55904
	s_waitcnt lgkmcnt(3)
	v_mfma_f32_32x32x16_bf16 v[16:31], v[206:209], v[224:227], v[16:31]
	ds_read_b128 v[206:209], v211 offset:60512
	s_waitcnt lgkmcnt(3)
	v_mfma_f32_32x32x16_bf16 v[0:15], v[244:247], v[224:227], v[0:15]
	ds_read_b128 v[244:247], v211 offset:65120
	s_waitcnt lgkmcnt(3)
	v_mfma_f32_32x32x16_bf16 v[48:63], v[232:235], v[228:231], v[48:63]
	s_waitcnt lgkmcnt(2)
	v_mfma_f32_32x32x16_bf16 v[32:47], v[202:205], v[228:231], v[32:47]
	s_waitcnt lgkmcnt(1)
	v_mfma_f32_32x32x16_bf16 v[16:31], v[206:209], v[228:231], v[16:31]
	s_waitcnt lgkmcnt(0)
	v_mfma_f32_32x32x16_bf16 v[0:15], v[244:247], v[228:231], v[0:15]

	.amdhsa_kernel _Z8yoco_fwd4Args
		.amdhsa_group_segment_fixed_size 0
		.amdhsa_private_segment_fixed_size 0
		.amdhsa_kernarg_size 480
		.amdhsa_user_sgpr_count 2
		.amdhsa_user_sgpr_dispatch_ptr 0
		.amdhsa_user_sgpr_queue_ptr 0
		.amdhsa_user_sgpr_kernarg_segment_ptr 1
		.amdhsa_user_sgpr_dispatch_id 0
		.amdhsa_user_sgpr_kernarg_preload_length 0
		.amdhsa_user_sgpr_kernarg_preload_offset 0
		.amdhsa_user_sgpr_private_segment_size 0
		.amdhsa_uses_dynamic_stack 0
		.amdhsa_enable_private_segment 0
		.amdhsa_system_sgpr_workgroup_id_x 1
		.amdhsa_system_sgpr_workgroup_id_y 0
		.amdhsa_system_sgpr_workgroup_id_z 0
		.amdhsa_system_sgpr_workgroup_info 0
		.amdhsa_system_vgpr_workitem_id 2
		.amdhsa_next_free_vgpr 256
		.amdhsa_next_free_sgpr 102
		.amdhsa_accum_offset 256
		.amdhsa_reserve_vcc 1
		.amdhsa_float_round_mode_32 0
		.amdhsa_float_round_mode_16_64 0
		.amdhsa_float_denorm_mode_32 3
		.amdhsa_float_denorm_mode_16_64 3
		.amdhsa_dx10_clamp 1
		.amdhsa_ieee_mode 1
		.amdhsa_fp16_overflow 0
		.amdhsa_tg_split 0
		.amdhsa_exception_fp_ieee_invalid_op 0
		.amdhsa_exception_fp_denorm_src 0
		.amdhsa_exception_fp_ieee_div_zero 0
		.amdhsa_exception_fp_ieee_overflow 0
		.amdhsa_exception_fp_ieee_underflow 0
		.amdhsa_exception_fp_ieee_inexact 0
		.amdhsa_exception_int_div_zero 0
	.end_amdhsa_kernel

amdhsa.kernels:
  - .agpr_count:     0
    .args:
      - .offset:         0
        .size:           224
        .value_kind:     by_value
      - .offset:         224
        .size:           4
        .value_kind:     hidden_block_count_x
      - .offset:         228
        .size:           4
        .value_kind:     hidden_block_count_y
      - .offset:         232
        .size:           4
        .value_kind:     hidden_block_count_z
      - .offset:         236
        .size:           2
        .value_kind:     hidden_group_size_x
      - .offset:         238
        .size:           2
        .value_kind:     hidden_group_size_y
      - .offset:         240
        .size:           2
        .value_kind:     hidden_group_size_z
      - .offset:         242
        .size:           2
        .value_kind:     hidden_remainder_x
      - .offset:         244
        .size:           2
        .value_kind:     hidden_remainder_y
      - .offset:         246
        .size:           2
        .value_kind:     hidden_remainder_z
      - .offset:         264
        .size:           8
        .value_kind:     hidden_global_offset_x
      - .offset:         272
        .size:           8
        .value_kind:     hidden_global_offset_y
      - .offset:         280
        .size:           8
        .value_kind:     hidden_global_offset_z
      - .offset:         288
        .size:           2
        .value_kind:     hidden_grid_dims
      - .offset:         312
        .size:           8
        .value_kind:     hidden_multigrid_sync_arg
      - .offset:         344
        .size:           4
        .value_kind:     hidden_dynamic_lds_size
    .group_segment_fixed_size: 0
    .kernarg_segment_align: 8
    .kernarg_segment_size: 480
    .language:       OpenCL C
    .language_version:
      - 2
      - 0
    .max_flat_workgroup_size: 512
    .name:           _Z8yoco_fwd4Args
    .private_segment_fixed_size: 0
    .sgpr_count:     108
    .sgpr_spill_count: 10
    .symbol:         _Z8yoco_fwd4Args.kd
    .uniform_work_group_size: 1
    .uses_dynamic_stack: false
    .vgpr_count:     256
    .vgpr_spill_count: 0
    .wavefront_size: 64
